# QK chunk operand also stored fragment-major (producer byte offsets bit-permuted), all x4 chunkrec loads lane-contiguous
# speedup vs baseline: 1.0215x; 1.0001x over previous
; __device__ __forceinline__ int opaque_tid() { int t = threadIdx.x; asm volatile("" : "+v"(t)); return t; }
; __device__ __forceinline__ int bid() { int b = blockIdx.x; asm volatile("" : "+s"(b)); return b; }
; __device__ __forceinline__ int gdim() { int g = gridDim.x; asm volatile("" : "+s"(g)); return g; }
; DI int xcd_group_item(int blk, int G) { if (G != 256) return blk; const int x = blk & 7, k = blk >> 3; return ((x + 8 * (k >> 2)) << 2) + (k & 3); }
; DI void phase_dn_chunkrec(PrmC p, unsigned char* smem) {
;     ...
;     const int tid = opaque_tid(), lane = tid & 63, wave = tid >> 6, r16 = lane & 15, q4 = lane >> 4, rt = wave >> 1, ct = wave & 1;
;     for (int item0 = bid(); item0 < 256; item0 += gdim()) {
;         const int item = xcd_group_item(item0, gdim());
;         const int sl = item & 3, dir = (item >> 2) & 1, h = (item >> 3) & 3, b = item >> 5, bh = b * 4 + h;
;         f32x4 Sacc[2];
;         Sacc[0] = (f32x4){0.f, 0.f, 0.f, 0.f}; Sacc[1] = Sacc[0];
;         __syncthreads();
;         for (int i = tid; i < 32 * DS_PITCH / 16; i += NTHR) *(uint4*)(smem + D_ST + i * 16) = make_uint4(0, 0, 0, 0);
;         uint4 wf0, wf1, wf2, wf3, qf0, qf1, qf2, qf3, qk0, qk1, kd00, kd01, kd10, kd11; uint2 uf;
;         uint4 nwf0, nwf1, nwf2, nwf3, nqf0, nqf1, nqf2, nqf3, nqk0, nqk1, nkd00, nkd01, nkd10, nkd11; uint2 nuf;
;     ...
;         if (tid < 36) ((float*)(smem + D_EG))[tid] = DEG[(size_t)dir * 1152 + bh * 36 + DC_CIDX(tid)];
.LBB0_286:
	s_andn2_b64 vcc, exec, s[6:7]
	s_cbranch_vccnz .LBB0_321
	s_waitcnt vmcnt(0)
	v_mov_b32_e32 v122, v195
	v_readlane_b32 s4, v254, 0
	s_cmpk_gt_i32 s4, 0xff
	s_cbranch_scc1 .LBB0_321
	v_bfe_u32 v11, v122, 4, 2
	v_lshlrev_b32_e32 v124, 4, v11
	v_mov_b32_e32 v125, v1
	v_lshl_add_u64 v[6:7], s[66:67], 0, v[124:125]
	s_mov_b64 s[12:13], 0x1f86a000
	v_lshl_add_u64 v[126:127], v[6:7], 0, s[12:13]
	s_mov_b64 s[12:13], 0x21c6a000
	v_ashrrev_i32_e32 v10, 7, v122
	v_lshl_add_u64 v[128:129], v[6:7], 0, s[12:13]
	s_mov_b64 s[12:13], 0x2646a000
	v_lshlrev_b32_e32 v2, 4, v10
	v_lshl_add_u64 v[130:131], v[6:7], 0, s[12:13]
	s_mov_b64 s[12:13], 0x2406a000
	v_ashrrev_i32_e32 v3, 31, v2
	v_lshl_add_u64 v[134:135], v[6:7], 0, s[12:13]
	v_lshrrev_b32_e32 v6, 2, v122
	v_and_b32_e32 v8, 15, v122
	v_lshlrev_b32_e32 v166, 11, v10
	v_lshl_add_u32 v166, v11, 7, v166
	v_lshlrev_b32_e32 v167, 3, v11
	v_sub_u32_e32 v166, v166, v167
	v_lshl_add_u32 v166, v8, 3, v166
	v_mov_b32_e32 v167, 0
	v_lshlrev_b32_e32 v168, 11, v10
	v_lshl_add_u32 v168, v11, 8, v168
	v_lshlrev_b32_e32 v169, 4, v11
	v_sub_u32_e32 v168, v168, v169
	v_lshl_add_u32 v168, v8, 4, v168
	v_mov_b32_e32 v169, 0
	v_mov_b32_e32 v5, v3
	v_lshlrev_b32_e32 v0, 3, v11
	v_and_b32_e32 v12, 16, v6
	v_lshl_add_u64 v[6:7], v[2:3], 1, s[66:67]
	v_lshlrev_b32_e32 v3, 2, v11
	v_or_b32_e32 v4, v2, v8
	v_lshlrev_b32_e32 v10, 5, v10
	v_lshl_add_u64 v[6:7], v[6:7], 0, v[0:1]
	s_mov_b64 s[12:13], 0x2766a000
	v_or_b32_e32 v2, v3, v2
	v_lshl_add_u32 v9, v8, 2, 0
	v_or_b32_e32 v132, v10, v8
	v_or_b32_e32 v125, v12, v8
	v_lshl_add_u64 v[136:137], v[6:7], 0, s[12:13]
	v_lshlrev_b32_e32 v7, 1, v2
	v_lshlrev_b32_e32 v8, 2, v12
	v_lshlrev_b32_e32 v2, 7, v2
	v_add3_u32 v155, v9, v8, v2
	v_max_i32_e32 v2, 32, v122
	v_sub_u32_e32 v2, v2, v122
	s_movk_i32 s12, 0x110
	v_add_u32_e32 v2, 0x1ff, v2
	s_add_u32 s5, s66, 0x2be6a000
	v_mad_u32_u24 v6, v125, s12, 0
	v_lshlrev_b32_e32 v0, 7, v125
	v_lshlrev_b64 v[138:139], 7, v[4:5]
	v_lshrrev_b32_e32 v4, 9, v2
	s_addc_u32 s25, s67, 0
	v_sub_u32_e32 v153, v6, v0
	v_lshlrev_b32_e32 v0, 3, v122
	v_add_u32_e32 v4, 1, v4
	s_add_u32 s27, s66, 0x1554a000
	s_movk_i32 s6, 0x220
	v_or_b32_e32 v3, v3, v10
	v_and_b32_e32 v0, 24, v0
	s_movk_i32 s12, 0x1ff
	v_and_b32_e32 v156, 0xfffffe, v4
	s_addc_u32 s28, s67, 0
	v_cmp_gt_i32_e64 s[6:7], s6, v122
	v_cmp_lt_i32_e64 s[8:9], 35, v122
	v_cmp_gt_i32_e64 s[10:11], 4, v122
	v_sub_u32_e32 v145, 39, v122
	v_sub_u32_e32 v150, 3, v122
	v_lshl_add_u32 v151, v122, 2, 0
	v_ashrrev_i32_e32 v133, 31, v10
	v_add_u32_e32 v152, v6, v124
	v_lshl_add_u32 v154, v0, 2, 0
	v_cmp_lt_u32_e64 s[12:13], s12, v2
	v_lshl_add_u32 v157, v156, 9, v122
	v_add_u32_e32 v123, 0x200, v122
	v_cmp_ne_u32_e64 s[14:15], v4, v156
	v_lshl_add_u32 v158, v3, 1, v6
	v_lshlrev_b32_e32 v0, 1, v0
	v_add_u32_e32 v159, v153, v7

; DI void phase_dn_chunkrec(PrmC p, unsigned char* smem) {
;     ...
;         if (tid < 36) ((float*)(smem + D_EG))[tid] = DEG[(size_t)dir * 1152 + bh * 36 + DC_CIDX(tid)];
;         DC_LOAD(0, );
;         __syncthreads();
.LBB0_301:
	s_or_b64 exec, exec, s[20:21]
	s_cmp_eq_u32 s31, 0
	s_cselect_b64 s[16:17], -1, 0
	s_and_b64 s[18:19], s[16:17], exec
	v_lshl_add_u64 v[142:143], v[60:61], 0, v[58:59]
	s_cselect_b32 s18, 0, 3
	v_or_b32_e32 v58, s18, v142
	v_mov_b32_e32 v59, v143
	v_lshlrev_b64 v[60:61], 13, v[58:59]
	v_lshl_add_u64 v[62:63], v[60:61], 0, v[166:167]
	v_lshl_add_u64 v[60:61], v[60:61], 0, v[168:169]
	v_lshlrev_b64 v[62:63], 1, v[62:63]
	v_lshl_add_u64 v[2:3], v[134:135], 0, v[62:63]
	v_lshl_add_u64 v[64:65], v[126:127], 0, v[62:63]
	v_lshl_add_u64 v[62:63], v[128:129], 0, v[62:63]
	global_load_dwordx4 v[114:117], v[64:65], off
	global_load_dwordx4 v[106:109], v[64:65], off offset:1024
	global_load_dwordx4 v[110:113], v[64:65], off offset:2048
	global_load_dwordx4 v[98:101], v[64:65], off offset:3072
	global_load_dwordx4 v[118:121], v[62:63], off
	global_load_dwordx4 v[102:105], v[62:63], off offset:1024
	global_load_dwordx4 v[94:97], v[62:63], off offset:2048
	global_load_dwordx4 v[90:93], v[62:63], off offset:3072
	v_lshl_add_u64 v[60:61], v[130:131], 0, v[60:61]
	v_lshlrev_b64 v[58:59], 7, v[58:59]
	s_lshl_b32 s18, s37, 5
	global_load_dwordx4 v[86:89], v[60:61], off
	global_load_dwordx4 v[82:85], v[60:61], off offset:1024
	v_lshl_add_u64 v[60:61], v[58:59], 0, v[132:133]
	s_and_b32 s18, s18, 0x60
	v_lshlrev_b64 v[60:61], 7, v[60:61]
	v_or_b32_e32 v144, s18, v125
	v_lshl_add_u64 v[60:61], v[134:135], 0, v[60:61]
	v_or_b32_e32 v58, v58, v144
	global_load_dwordx4 v[70:73], v[2:3], off
	global_load_dwordx4 v[78:81], v[2:3], off offset:1024
	global_load_dwordx4 v[74:77], v[2:3], off offset:2048
	global_load_dwordx4 v[66:69], v[2:3], off offset:3072
	v_lshlrev_b64 v[58:59], 7, v[58:59]
	v_lshl_add_u64 v[58:59], v[136:137], 0, v[58:59]
	global_load_dwordx2 v[148:149], v[58:59], off
	s_lshl_b32 s18, s18, 1
	s_add_u32 s20, s27, s18
	s_addc_u32 s21, s28, 0
	s_lshl_b32 s29, s29, 8
	s_add_u32 s20, s20, s29
	s_addc_u32 s21, s21, 0
	s_lshl_b32 s37, s30, 8
	v_mov_b32_e32 v58, 0
	s_mov_b32 s39, 0
	s_mul_i32 s18, s31, 0x4800
	s_mov_b32 s19, s36
	v_lshl_add_u64 v[146:147], s[20:21], 0, v[0:1]
	s_lshl_b32 s29, s30, 11
	s_addk_i32 s37, 0x4000
	v_mov_b32_e32 v59, v58
	v_mov_b32_e32 v60, v58
	v_mov_b32_e32 v61, v58
	v_mov_b32_e32 v62, v58
	v_mov_b32_e32 v63, v58
	v_mov_b32_e32 v64, v58
	v_mov_b32_e32 v65, v58
	s_waitcnt lgkmcnt(0)
	s_barrier
	s_add_i32 s38, s39, 1
	s_cmp_eq_u32 s39, 35
	s_cbranch_scc1 .LBB0_308
	s_branch .LBB0_303

; DI void phase_dn_chunkrec(PrmC p, unsigned char* smem) {
;     ...
;         if (tid < 36) ((float*)(smem + D_EG))[tid] = DEG[(size_t)dir * 1152 + bh * 36 + DC_CIDX(tid)];
;         DC_LOAD(0, );
;         __syncthreads();
; #pragma unroll 1
;         for (int ch = 0; ch < 36; ++ch) {
;             if (ch + 1 < 36) DC_LOAD(ch + 1, n);
.LBB0_307:
	s_mov_b32 s21, s36
	v_lshl_add_u64 v[42:43], v[142:143], 0, s[20:21]
	v_lshlrev_b64 v[2:3], 13, v[42:43]
	v_lshl_add_u64 v[34:35], v[2:3], 0, v[168:169]
	v_lshl_add_u64 v[2:3], v[2:3], 0, v[166:167]
	v_lshlrev_b64 v[2:3], 1, v[2:3]
	v_lshl_add_u64 v[14:15], v[126:127], 0, v[2:3]
	v_lshl_add_u64 v[30:31], v[128:129], 0, v[2:3]
	v_lshl_add_u64 v[54:55], v[134:135], 0, v[2:3]
	global_load_dwordx4 v[2:5], v[14:15], off
	global_load_dwordx4 v[6:9], v[14:15], off offset:1024
	global_load_dwordx4 v[10:13], v[14:15], off offset:2048
	s_nop 0
	global_load_dwordx4 v[14:17], v[14:15], off offset:3072
	s_nop 0
	global_load_dwordx4 v[18:21], v[30:31], off
	global_load_dwordx4 v[22:25], v[30:31], off offset:1024
	global_load_dwordx4 v[26:29], v[30:31], off offset:2048
	s_nop 0
	global_load_dwordx4 v[30:33], v[30:31], off offset:3072
	v_lshlrev_b64 v[140:141], 7, v[42:43]
	v_lshl_add_u64 v[42:43], v[140:141], 0, v[132:133]
	v_lshlrev_b64 v[42:43], 7, v[42:43]
	v_lshl_add_u64 v[38:39], v[130:131], 0, v[34:35]
	v_or_b32_e32 v140, v140, v144
	global_load_dwordx4 v[34:37], v[38:39], off
	s_nop 0
	global_load_dwordx4 v[38:41], v[38:39], off offset:1024
	s_nop 0
	global_load_dwordx4 v[42:45], v[54:55], off
	global_load_dwordx4 v[46:49], v[54:55], off offset:1024
	global_load_dwordx4 v[50:53], v[54:55], off offset:2048
	s_nop 0
	global_load_dwordx4 v[54:57], v[54:55], off offset:3072
	v_lshlrev_b64 v[140:141], 7, v[140:141]
	v_lshl_add_u64 v[140:141], v[136:137], 0, v[140:141]
	global_load_dwordx2 v[140:141], v[140:141], off

; DI unsigned f2bf(float f) { unsigned u = __float_as_uint(f); return (u + 0x7fffu + ((u >> 16) & 1u)) >> 16; }
; DI void phase_dn_chunkprep(PrmC p, unsigned char* smem, int vb, int nvb) {
;     ...
;                 bf16_t* q0 = DQK + ((size_t)item * 64) * 64; bf16_t* q1 = DQK + ((size_t)(1152 + item) * 64) * 64;
; #pragma unroll
;                 for (int i = 0; i < 16; ++i) { const int ni = 32 * it + (i & 3) + 8 * (i >> 2) + 4 * hh;
;                     const float v0 = ni >= nj ? acc[i] * __expf(Gn[ni] - g0j) : 0.f, v1 = ni <= nj ? acc[i] * __expf(Gn[64 + ni] - g1j) : 0.f;
;                     q0[ni * 64 + nj] = (bf16_t)f2bf(v0); q1[(63 - ni) * 64 + (63 - nj)] = (bf16_t)f2bf(v1); }
.LBB0_483:
	s_or_b64 exec, exec, s[44:45]
	s_add_i32 s28, s38, 0x480
	s_ashr_i32 s29, s28, 31
	s_lshl_b64 s[28:29], s[28:29], 13
	s_add_u32 s44, s93, s28
	s_addc_u32 s45, s5, s29
	v_bfe_u32 v2, v0, 16, 1
	v_lshlrev_b32_e32 v30, 6, v25
	v_add3_u32 v2, v0, v2, s71
	v_or_b32_e32 v0, v30, v24
	s_add_u32 s28, s66, s16
	v_lshlrev_b32_e32 v0, 1, v0
	v_lshrrev_b32_e32 v226, 3, v0
	v_lshlrev_b32_e32 v227, 4, v0
	v_and_b32_e32 v226, 0xf0, v226
	v_and_b32_e32 v227, 0x700, v227
	v_and_b32_e32 v0, 0x180f, v0
	v_or3_b32 v0, v0, v226, v227
	s_addc_u32 s29, s67, s17
	v_lshl_add_u64 v[28:29], s[28:29], 0, v[0:1]
	v_add_co_u32_e32 v28, vcc, 0x2646a000, v28
	s_movk_i32 s27, 0x93f
	s_nop 0
	v_addc_co_u32_e32 v29, vcc, 0, v29, vcc
	global_store_short_d16_hi v[28:29], v2, off
	v_bfe_u32 v0, v27, 16, 1
	v_bitop3_b32 v2, v30, s27, v24 bitop3:0x36
	v_add3_u32 v0, v27, v0, s71
	v_lshlrev_b32_e32 v2, 1, v2
	v_add_u32_e32 v2, 3456, v2
	v_lshrrev_b32_e32 v226, 3, v2
	v_lshlrev_b32_e32 v227, 4, v2
	v_and_b32_e32 v226, 0xf0, v226
	v_and_b32_e32 v227, 0x700, v227
	v_and_b32_e32 v2, 0x180f, v2
	v_or3_b32 v2, v2, v226, v227
	global_store_short_d16_hi v2, v0, s[44:45]
	v_or_b32_e32 v0, 1, v25
	v_cmp_ge_u32_e32 vcc, v0, v24
	v_mov_b32_e32 v2, 0
	v_mov_b32_e32 v27, 0
	s_and_saveexec_b64 s[46:47], vcc
	s_cbranch_execz .LBB0_485
	ds_read_b32 v27, v26 offset:4
	s_waitcnt lgkmcnt(0)
	v_sub_f32_e32 v27, v27, v22
	v_mul_f32_e32 v27, 0x3fb8aa3b, v27
	v_exp_f32_e32 v27, v27
	s_nop 0
	v_mul_f32_e32 v27, v3, v27

; DI unsigned f2bf(float f) { unsigned u = __float_as_uint(f); return (u + 0x7fffu + ((u >> 16) & 1u)) >> 16; }
; DI void phase_dn_chunkprep(PrmC p, unsigned char* smem, int vb, int nvb) {
;     ...
;                 bf16_t* q0 = DQK + ((size_t)item * 64) * 64; bf16_t* q1 = DQK + ((size_t)(1152 + item) * 64) * 64;
; #pragma unroll
;                 for (int i = 0; i < 16; ++i) { const int ni = 32 * it + (i & 3) + 8 * (i >> 2) + 4 * hh;
;                     const float v0 = ni >= nj ? acc[i] * __expf(Gn[ni] - g0j) : 0.f, v1 = ni <= nj ? acc[i] * __expf(Gn[64 + ni] - g1j) : 0.f;
;                     q0[ni * 64 + nj] = (bf16_t)f2bf(v0); q1[(63 - ni) * 64 + (63 - nj)] = (bf16_t)f2bf(v1); }
.LBB0_487:
	s_or_b64 exec, exec, s[46:47]
	v_bfe_u32 v3, v27, 16, 1
	v_add3_u32 v3, v27, v3, s71
	v_lshlrev_b32_e32 v27, 6, v0
	v_or_b32_e32 v0, v27, v24
	s_add_u32 s20, s66, s16
	v_lshlrev_b32_e32 v0, 1, v0
	v_lshrrev_b32_e32 v226, 3, v0
	v_lshlrev_b32_e32 v227, 4, v0
	v_and_b32_e32 v226, 0xf0, v226
	v_and_b32_e32 v227, 0x700, v227
	v_and_b32_e32 v0, 0x180f, v0
	v_or3_b32 v0, v0, v226, v227
	s_addc_u32 s21, s67, s17
	v_lshl_add_u64 v[28:29], s[20:21], 0, v[0:1]
	v_bfe_u32 v0, v2, 16, 1
	s_movk_i32 s20, 0x97f
	v_add_co_u32_e32 v28, vcc, 0x2646a000, v28
	v_add3_u32 v0, v2, v0, s71
	v_bitop3_b32 v2, v27, s20, v24 bitop3:0x36
	v_addc_co_u32_e32 v29, vcc, 0, v29, vcc
	v_lshlrev_b32_e32 v2, 1, v2
	v_add_u32_e32 v2, 3328, v2
	v_lshrrev_b32_e32 v226, 3, v2
	v_lshlrev_b32_e32 v227, 4, v2
	v_and_b32_e32 v226, 0xf0, v226
	v_and_b32_e32 v227, 0x700, v227
	v_and_b32_e32 v2, 0x180f, v2
	v_or3_b32 v2, v2, v226, v227
	global_store_short_d16_hi v[28:29], v3, off
	global_store_short_d16_hi v2, v0, s[44:45]
	v_or_b32_e32 v0, 2, v25
	v_cmp_ge_u32_e32 vcc, v0, v24
	v_mov_b32_e32 v2, 0
	v_mov_b32_e32 v3, 0
	s_and_saveexec_b64 s[20:21], vcc
	s_cbranch_execz .LBB0_489
	ds_read_b32 v3, v26 offset:8
	s_waitcnt lgkmcnt(0)
	v_sub_f32_e32 v3, v3, v22
	v_mul_f32_e32 v3, 0x3fb8aa3b, v3
	v_exp_f32_e32 v3, v3
	s_nop 0
	v_mul_f32_e32 v3, v4, v3

; DI unsigned f2bf(float f) { unsigned u = __float_as_uint(f); return (u + 0x7fffu + ((u >> 16) & 1u)) >> 16; }
; DI void phase_dn_chunkprep(PrmC p, unsigned char* smem, int vb, int nvb) {
;     ...
;                 bf16_t* q0 = DQK + ((size_t)item * 64) * 64; bf16_t* q1 = DQK + ((size_t)(1152 + item) * 64) * 64;
; #pragma unroll
;                 for (int i = 0; i < 16; ++i) { const int ni = 32 * it + (i & 3) + 8 * (i >> 2) + 4 * hh;
;                     const float v0 = ni >= nj ? acc[i] * __expf(Gn[ni] - g0j) : 0.f, v1 = ni <= nj ? acc[i] * __expf(Gn[64 + ni] - g1j) : 0.f;
;                     q0[ni * 64 + nj] = (bf16_t)f2bf(v0); q1[(63 - ni) * 64 + (63 - nj)] = (bf16_t)f2bf(v1); }
.LBB0_491:
	s_or_b64 exec, exec, s[20:21]
	v_bfe_u32 v4, v3, 16, 1
	v_add3_u32 v3, v3, v4, s71
	v_lshlrev_b32_e32 v4, 6, v0
	v_or_b32_e32 v0, v4, v24
	s_add_u32 s20, s66, s16
	v_lshlrev_b32_e32 v0, 1, v0
	v_lshrrev_b32_e32 v226, 3, v0
	v_lshlrev_b32_e32 v227, 4, v0
	v_and_b32_e32 v226, 0xf0, v226
	v_and_b32_e32 v227, 0x700, v227
	v_and_b32_e32 v0, 0x180f, v0
	v_or3_b32 v0, v0, v226, v227
	s_addc_u32 s21, s67, s17
	v_lshl_add_u64 v[28:29], s[20:21], 0, v[0:1]
	v_bfe_u32 v0, v2, 16, 1
	s_movk_i32 s20, 0x9bf
	v_add_co_u32_e32 v28, vcc, 0x2646a000, v28
	v_add3_u32 v0, v2, v0, s71
	v_bitop3_b32 v2, v4, s20, v24 bitop3:0x36
	v_addc_co_u32_e32 v29, vcc, 0, v29, vcc
	v_lshlrev_b32_e32 v2, 1, v2
	v_add_u32_e32 v2, 3200, v2
	v_lshrrev_b32_e32 v226, 3, v2
	v_lshlrev_b32_e32 v227, 4, v2
	v_and_b32_e32 v226, 0xf0, v226
	v_and_b32_e32 v227, 0x700, v227
	v_and_b32_e32 v2, 0x180f, v2
	v_or3_b32 v2, v2, v226, v227
	global_store_short_d16_hi v[28:29], v3, off
	global_store_short_d16_hi v2, v0, s[44:45]
	v_or_b32_e32 v0, 3, v25
	v_cmp_ge_u32_e32 vcc, v0, v24
	v_mov_b32_e32 v2, 0
	v_mov_b32_e32 v3, 0
	s_and_saveexec_b64 s[20:21], vcc
	s_cbranch_execz .LBB0_493
	ds_read_b32 v3, v26 offset:12
	s_waitcnt lgkmcnt(0)
	v_sub_f32_e32 v3, v3, v22
	v_mul_f32_e32 v3, 0x3fb8aa3b, v3
	v_exp_f32_e32 v3, v3
	s_nop 0
	v_mul_f32_e32 v3, v5, v3

; DI unsigned f2bf(float f) { unsigned u = __float_as_uint(f); return (u + 0x7fffu + ((u >> 16) & 1u)) >> 16; }
; DI void phase_dn_chunkprep(PrmC p, unsigned char* smem, int vb, int nvb) {
;     ...
;                 bf16_t* q0 = DQK + ((size_t)item * 64) * 64; bf16_t* q1 = DQK + ((size_t)(1152 + item) * 64) * 64;
; #pragma unroll
;                 for (int i = 0; i < 16; ++i) { const int ni = 32 * it + (i & 3) + 8 * (i >> 2) + 4 * hh;
;                     const float v0 = ni >= nj ? acc[i] * __expf(Gn[ni] - g0j) : 0.f, v1 = ni <= nj ? acc[i] * __expf(Gn[64 + ni] - g1j) : 0.f;
;                     q0[ni * 64 + nj] = (bf16_t)f2bf(v0); q1[(63 - ni) * 64 + (63 - nj)] = (bf16_t)f2bf(v1); }
.LBB0_495:
	s_or_b64 exec, exec, s[20:21]
	v_lshlrev_b32_e32 v27, 6, v0
	v_or_b32_e32 v0, v27, v24
	s_add_u32 s20, s66, s16
	v_bfe_u32 v4, v3, 16, 1
	v_lshlrev_b32_e32 v0, 1, v0
	v_lshrrev_b32_e32 v226, 3, v0
	v_lshlrev_b32_e32 v227, 4, v0
	v_and_b32_e32 v226, 0xf0, v226
	v_and_b32_e32 v227, 0x700, v227
	v_and_b32_e32 v0, 0x180f, v0
	v_or3_b32 v0, v0, v226, v227
	s_addc_u32 s21, s67, s17
	v_add3_u32 v3, v3, v4, s71
	v_lshl_add_u64 v[4:5], s[20:21], 0, v[0:1]
	v_bfe_u32 v0, v2, 16, 1
	s_movk_i32 s20, 0x9ff
	v_add_co_u32_e32 v4, vcc, 0x2646a000, v4
	v_add3_u32 v0, v2, v0, s71
	v_bitop3_b32 v2, v27, s20, v24 bitop3:0x36
	v_addc_co_u32_e32 v5, vcc, 0, v5, vcc
	v_lshlrev_b32_e32 v2, 1, v2
	v_add_u32_e32 v2, 3072, v2
	v_lshrrev_b32_e32 v226, 3, v2
	v_lshlrev_b32_e32 v227, 4, v2
	v_and_b32_e32 v226, 0xf0, v226
	v_and_b32_e32 v227, 0x700, v227
	v_and_b32_e32 v2, 0x180f, v2
	v_or3_b32 v2, v2, v226, v227
	global_store_short_d16_hi v[4:5], v3, off
	global_store_short_d16_hi v2, v0, s[44:45]
	v_or_b32_e32 v0, 8, v25
	v_cmp_ge_u32_e32 vcc, v0, v24
	v_mov_b32_e32 v2, 0
	v_mov_b32_e32 v3, 0
	s_and_saveexec_b64 s[20:21], vcc
	s_cbranch_execz .LBB0_497
	ds_read_b32 v3, v26 offset:32
	s_waitcnt lgkmcnt(0)
	v_sub_f32_e32 v3, v3, v22
	v_mul_f32_e32 v3, 0x3fb8aa3b, v3
	v_exp_f32_e32 v3, v3
	s_nop 0
	v_mul_f32_e32 v3, v6, v3

; DI unsigned f2bf(float f) { unsigned u = __float_as_uint(f); return (u + 0x7fffu + ((u >> 16) & 1u)) >> 16; }
; DI void phase_dn_chunkprep(PrmC p, unsigned char* smem, int vb, int nvb) {
;     ...
;                 bf16_t* q0 = DQK + ((size_t)item * 64) * 64; bf16_t* q1 = DQK + ((size_t)(1152 + item) * 64) * 64;
; #pragma unroll
;                 for (int i = 0; i < 16; ++i) { const int ni = 32 * it + (i & 3) + 8 * (i >> 2) + 4 * hh;
;                     const float v0 = ni >= nj ? acc[i] * __expf(Gn[ni] - g0j) : 0.f, v1 = ni <= nj ? acc[i] * __expf(Gn[64 + ni] - g1j) : 0.f;
;                     q0[ni * 64 + nj] = (bf16_t)f2bf(v0); q1[(63 - ni) * 64 + (63 - nj)] = (bf16_t)f2bf(v1); }
.LBB0_499:
	s_or_b64 exec, exec, s[20:21]
	v_lshlrev_b32_e32 v6, 6, v0
	v_or_b32_e32 v0, v6, v24
	s_add_u32 s20, s66, s16
	v_bfe_u32 v4, v3, 16, 1
	v_lshlrev_b32_e32 v0, 1, v0
	v_lshrrev_b32_e32 v226, 3, v0
	v_lshlrev_b32_e32 v227, 4, v0
	v_and_b32_e32 v226, 0xf0, v226
	v_and_b32_e32 v227, 0x700, v227
	v_and_b32_e32 v0, 0x180f, v0
	v_or3_b32 v0, v0, v226, v227
	s_addc_u32 s21, s67, s17
	v_add3_u32 v3, v3, v4, s71
	v_lshl_add_u64 v[4:5], s[20:21], 0, v[0:1]
	v_bfe_u32 v0, v2, 16, 1
	s_movk_i32 s20, 0xb3f
	v_add_co_u32_e32 v4, vcc, 0x2646a000, v4
	v_add3_u32 v0, v2, v0, s71
	v_bitop3_b32 v2, v6, s20, v24 bitop3:0x36
	v_addc_co_u32_e32 v5, vcc, 0, v5, vcc
	v_lshlrev_b32_e32 v2, 1, v2
	v_add_u32_e32 v2, 2432, v2
	v_lshrrev_b32_e32 v226, 3, v2
	v_lshlrev_b32_e32 v227, 4, v2
	v_and_b32_e32 v226, 0xf0, v226
	v_and_b32_e32 v227, 0x700, v227
	v_and_b32_e32 v2, 0x180f, v2
	v_or3_b32 v2, v2, v226, v227
	global_store_short_d16_hi v[4:5], v3, off
	global_store_short_d16_hi v2, v0, s[44:45]
	v_or_b32_e32 v0, 9, v25
	v_cmp_ge_u32_e32 vcc, v0, v24
	v_mov_b32_e32 v2, 0
	v_mov_b32_e32 v3, 0
	s_and_saveexec_b64 s[20:21], vcc
	s_cbranch_execz .LBB0_501
	ds_read_b32 v3, v26 offset:36
	s_waitcnt lgkmcnt(0)
	v_sub_f32_e32 v3, v3, v22
	v_mul_f32_e32 v3, 0x3fb8aa3b, v3
	v_exp_f32_e32 v3, v3
	s_nop 0
	v_mul_f32_e32 v3, v7, v3

; DI unsigned f2bf(float f) { unsigned u = __float_as_uint(f); return (u + 0x7fffu + ((u >> 16) & 1u)) >> 16; }
; DI void phase_dn_chunkprep(PrmC p, unsigned char* smem, int vb, int nvb) {
;     ...
;                 bf16_t* q0 = DQK + ((size_t)item * 64) * 64; bf16_t* q1 = DQK + ((size_t)(1152 + item) * 64) * 64;
; #pragma unroll
;                 for (int i = 0; i < 16; ++i) { const int ni = 32 * it + (i & 3) + 8 * (i >> 2) + 4 * hh;
;                     const float v0 = ni >= nj ? acc[i] * __expf(Gn[ni] - g0j) : 0.f, v1 = ni <= nj ? acc[i] * __expf(Gn[64 + ni] - g1j) : 0.f;
;                     q0[ni * 64 + nj] = (bf16_t)f2bf(v0); q1[(63 - ni) * 64 + (63 - nj)] = (bf16_t)f2bf(v1); }
.LBB0_503:
	s_or_b64 exec, exec, s[20:21]
	v_lshlrev_b32_e32 v6, 6, v0
	v_or_b32_e32 v0, v6, v24
	s_add_u32 s20, s66, s16
	v_bfe_u32 v4, v3, 16, 1
	v_lshlrev_b32_e32 v0, 1, v0
	v_lshrrev_b32_e32 v226, 3, v0
	v_lshlrev_b32_e32 v227, 4, v0
	v_and_b32_e32 v226, 0xf0, v226
	v_and_b32_e32 v227, 0x700, v227
	v_and_b32_e32 v0, 0x180f, v0
	v_or3_b32 v0, v0, v226, v227
	s_addc_u32 s21, s67, s17
	v_add3_u32 v3, v3, v4, s71
	v_lshl_add_u64 v[4:5], s[20:21], 0, v[0:1]
	v_bfe_u32 v0, v2, 16, 1
	s_movk_i32 s20, 0xb7f
	v_add_co_u32_e32 v4, vcc, 0x2646a000, v4
	v_add3_u32 v0, v2, v0, s71
	v_bitop3_b32 v2, v6, s20, v24 bitop3:0x36
	v_addc_co_u32_e32 v5, vcc, 0, v5, vcc
	v_lshlrev_b32_e32 v2, 1, v2
	v_add_u32_e32 v2, 2304, v2
	v_lshrrev_b32_e32 v226, 3, v2
	v_lshlrev_b32_e32 v227, 4, v2
	v_and_b32_e32 v226, 0xf0, v226
	v_and_b32_e32 v227, 0x700, v227
	v_and_b32_e32 v2, 0x180f, v2
	v_or3_b32 v2, v2, v226, v227
	global_store_short_d16_hi v[4:5], v3, off
	global_store_short_d16_hi v2, v0, s[44:45]
	v_or_b32_e32 v0, 10, v25
	v_cmp_ge_u32_e32 vcc, v0, v24
	v_mov_b32_e32 v2, 0
	v_mov_b32_e32 v3, 0
	s_and_saveexec_b64 s[20:21], vcc
	s_cbranch_execz .LBB0_505
	ds_read_b32 v3, v26 offset:40
	s_waitcnt lgkmcnt(0)
	v_sub_f32_e32 v3, v3, v22
	v_mul_f32_e32 v3, 0x3fb8aa3b, v3
	v_exp_f32_e32 v3, v3
	s_nop 0
	v_mul_f32_e32 v3, v8, v3

; DI unsigned f2bf(float f) { unsigned u = __float_as_uint(f); return (u + 0x7fffu + ((u >> 16) & 1u)) >> 16; }
; DI void phase_dn_chunkprep(PrmC p, unsigned char* smem, int vb, int nvb) {
;     ...
;                 bf16_t* q0 = DQK + ((size_t)item * 64) * 64; bf16_t* q1 = DQK + ((size_t)(1152 + item) * 64) * 64;
; #pragma unroll
;                 for (int i = 0; i < 16; ++i) { const int ni = 32 * it + (i & 3) + 8 * (i >> 2) + 4 * hh;
;                     const float v0 = ni >= nj ? acc[i] * __expf(Gn[ni] - g0j) : 0.f, v1 = ni <= nj ? acc[i] * __expf(Gn[64 + ni] - g1j) : 0.f;
;                     q0[ni * 64 + nj] = (bf16_t)f2bf(v0); q1[(63 - ni) * 64 + (63 - nj)] = (bf16_t)f2bf(v1); }
.LBB0_507:
	s_or_b64 exec, exec, s[20:21]
	v_lshlrev_b32_e32 v6, 6, v0
	v_or_b32_e32 v0, v6, v24
	s_add_u32 s20, s66, s16
	v_bfe_u32 v4, v3, 16, 1
	v_lshlrev_b32_e32 v0, 1, v0
	v_lshrrev_b32_e32 v226, 3, v0
	v_lshlrev_b32_e32 v227, 4, v0
	v_and_b32_e32 v226, 0xf0, v226
	v_and_b32_e32 v227, 0x700, v227
	v_and_b32_e32 v0, 0x180f, v0
	v_or3_b32 v0, v0, v226, v227
	s_addc_u32 s21, s67, s17
	v_add3_u32 v3, v3, v4, s71
	v_lshl_add_u64 v[4:5], s[20:21], 0, v[0:1]
	v_bfe_u32 v0, v2, 16, 1
	s_movk_i32 s20, 0xbbf
	v_add_co_u32_e32 v4, vcc, 0x2646a000, v4
	v_add3_u32 v0, v2, v0, s71
	v_bitop3_b32 v2, v6, s20, v24 bitop3:0x36
	v_addc_co_u32_e32 v5, vcc, 0, v5, vcc
	v_lshlrev_b32_e32 v2, 1, v2
	v_add_u32_e32 v2, 2176, v2
	v_lshrrev_b32_e32 v226, 3, v2
	v_lshlrev_b32_e32 v227, 4, v2
	v_and_b32_e32 v226, 0xf0, v226
	v_and_b32_e32 v227, 0x700, v227
	v_and_b32_e32 v2, 0x180f, v2
	v_or3_b32 v2, v2, v226, v227
	global_store_short_d16_hi v[4:5], v3, off
	global_store_short_d16_hi v2, v0, s[44:45]
	v_or_b32_e32 v0, 11, v25
	v_cmp_ge_u32_e32 vcc, v0, v24
	v_mov_b32_e32 v2, 0
	v_mov_b32_e32 v3, 0
	s_and_saveexec_b64 s[20:21], vcc
	s_cbranch_execz .LBB0_509
	ds_read_b32 v3, v26 offset:44
	s_waitcnt lgkmcnt(0)
	v_sub_f32_e32 v3, v3, v22
	v_mul_f32_e32 v3, 0x3fb8aa3b, v3
	v_exp_f32_e32 v3, v3
	s_nop 0
	v_mul_f32_e32 v3, v9, v3

; DI unsigned f2bf(float f) { unsigned u = __float_as_uint(f); return (u + 0x7fffu + ((u >> 16) & 1u)) >> 16; }
; DI void phase_dn_chunkprep(PrmC p, unsigned char* smem, int vb, int nvb) {
;     ...
;                 bf16_t* q0 = DQK + ((size_t)item * 64) * 64; bf16_t* q1 = DQK + ((size_t)(1152 + item) * 64) * 64;
; #pragma unroll
;                 for (int i = 0; i < 16; ++i) { const int ni = 32 * it + (i & 3) + 8 * (i >> 2) + 4 * hh;
;                     const float v0 = ni >= nj ? acc[i] * __expf(Gn[ni] - g0j) : 0.f, v1 = ni <= nj ? acc[i] * __expf(Gn[64 + ni] - g1j) : 0.f;
;                     q0[ni * 64 + nj] = (bf16_t)f2bf(v0); q1[(63 - ni) * 64 + (63 - nj)] = (bf16_t)f2bf(v1); }
.LBB0_511:
	s_or_b64 exec, exec, s[20:21]
	v_lshlrev_b32_e32 v6, 6, v0
	v_or_b32_e32 v0, v6, v24
	s_add_u32 s20, s66, s16
	v_bfe_u32 v4, v3, 16, 1
	v_lshlrev_b32_e32 v0, 1, v0
	v_lshrrev_b32_e32 v226, 3, v0
	v_lshlrev_b32_e32 v227, 4, v0
	v_and_b32_e32 v226, 0xf0, v226
	v_and_b32_e32 v227, 0x700, v227
	v_and_b32_e32 v0, 0x180f, v0
	v_or3_b32 v0, v0, v226, v227
	s_addc_u32 s21, s67, s17
	v_add3_u32 v3, v3, v4, s71
	v_lshl_add_u64 v[4:5], s[20:21], 0, v[0:1]
	v_bfe_u32 v0, v2, 16, 1
	s_movk_i32 s20, 0xbff
	v_add_co_u32_e32 v4, vcc, 0x2646a000, v4
	v_add3_u32 v0, v2, v0, s71
	v_bitop3_b32 v2, v6, s20, v24 bitop3:0x36
	v_addc_co_u32_e32 v5, vcc, 0, v5, vcc
	v_lshlrev_b32_e32 v2, 1, v2
	v_add_u32_e32 v2, 2048, v2
	v_lshrrev_b32_e32 v226, 3, v2
	v_lshlrev_b32_e32 v227, 4, v2
	v_and_b32_e32 v226, 0xf0, v226
	v_and_b32_e32 v227, 0x700, v227
	v_and_b32_e32 v2, 0x180f, v2
	v_or3_b32 v2, v2, v226, v227
	global_store_short_d16_hi v[4:5], v3, off
	global_store_short_d16_hi v2, v0, s[44:45]
	v_or_b32_e32 v0, 16, v25
	v_cmp_ge_u32_e32 vcc, v0, v24
	v_mov_b32_e32 v2, 0
	v_mov_b32_e32 v3, 0
	s_and_saveexec_b64 s[20:21], vcc
	s_cbranch_execz .LBB0_513
	ds_read_b32 v3, v26 offset:64
	s_waitcnt lgkmcnt(0)
	v_sub_f32_e32 v3, v3, v22
	v_mul_f32_e32 v3, 0x3fb8aa3b, v3
	v_exp_f32_e32 v3, v3
	s_nop 0
	v_mul_f32_e32 v3, v10, v3

; DI unsigned f2bf(float f) { unsigned u = __float_as_uint(f); return (u + 0x7fffu + ((u >> 16) & 1u)) >> 16; }
; DI void phase_dn_chunkprep(PrmC p, unsigned char* smem, int vb, int nvb) {
;     ...
;                 bf16_t* q0 = DQK + ((size_t)item * 64) * 64; bf16_t* q1 = DQK + ((size_t)(1152 + item) * 64) * 64;
; #pragma unroll
;                 for (int i = 0; i < 16; ++i) { const int ni = 32 * it + (i & 3) + 8 * (i >> 2) + 4 * hh;
;                     const float v0 = ni >= nj ? acc[i] * __expf(Gn[ni] - g0j) : 0.f, v1 = ni <= nj ? acc[i] * __expf(Gn[64 + ni] - g1j) : 0.f;
;                     q0[ni * 64 + nj] = (bf16_t)f2bf(v0); q1[(63 - ni) * 64 + (63 - nj)] = (bf16_t)f2bf(v1); }
.LBB0_515:
	s_or_b64 exec, exec, s[20:21]
	v_lshlrev_b32_e32 v6, 6, v0
	v_or_b32_e32 v0, v6, v24
	s_add_u32 s20, s66, s16
	v_bfe_u32 v4, v3, 16, 1
	v_lshlrev_b32_e32 v0, 1, v0
	v_lshrrev_b32_e32 v226, 3, v0
	v_lshlrev_b32_e32 v227, 4, v0
	v_and_b32_e32 v226, 0xf0, v226
	v_and_b32_e32 v227, 0x700, v227
	v_and_b32_e32 v0, 0x180f, v0
	v_or3_b32 v0, v0, v226, v227
	s_addc_u32 s21, s67, s17
	v_add3_u32 v3, v3, v4, s71
	v_lshl_add_u64 v[4:5], s[20:21], 0, v[0:1]
	v_bfe_u32 v0, v2, 16, 1
	s_movk_i32 s20, 0xd3f
	v_add_co_u32_e32 v4, vcc, 0x2646a000, v4
	v_add3_u32 v0, v2, v0, s71
	v_bitop3_b32 v2, v6, s20, v24 bitop3:0x36
	v_addc_co_u32_e32 v5, vcc, 0, v5, vcc
	v_lshlrev_b32_e32 v2, 1, v2
	v_add_u32_e32 v2, 1408, v2
	v_lshrrev_b32_e32 v226, 3, v2
	v_lshlrev_b32_e32 v227, 4, v2
	v_and_b32_e32 v226, 0xf0, v226
	v_and_b32_e32 v227, 0x700, v227
	v_and_b32_e32 v2, 0x180f, v2
	v_or3_b32 v2, v2, v226, v227
	global_store_short_d16_hi v[4:5], v3, off
	global_store_short_d16_hi v2, v0, s[44:45]
	v_or_b32_e32 v0, 17, v25
	v_cmp_ge_u32_e32 vcc, v0, v24
	v_mov_b32_e32 v2, 0
	v_mov_b32_e32 v3, 0
	s_and_saveexec_b64 s[20:21], vcc
	s_cbranch_execz .LBB0_517
	ds_read_b32 v3, v26 offset:68
	s_waitcnt lgkmcnt(0)
	v_sub_f32_e32 v3, v3, v22
	v_mul_f32_e32 v3, 0x3fb8aa3b, v3
	v_exp_f32_e32 v3, v3
	s_nop 0
	v_mul_f32_e32 v3, v11, v3

; DI unsigned f2bf(float f) { unsigned u = __float_as_uint(f); return (u + 0x7fffu + ((u >> 16) & 1u)) >> 16; }
; DI void phase_dn_chunkprep(PrmC p, unsigned char* smem, int vb, int nvb) {
;     ...
;                 bf16_t* q0 = DQK + ((size_t)item * 64) * 64; bf16_t* q1 = DQK + ((size_t)(1152 + item) * 64) * 64;
; #pragma unroll
;                 for (int i = 0; i < 16; ++i) { const int ni = 32 * it + (i & 3) + 8 * (i >> 2) + 4 * hh;
;                     const float v0 = ni >= nj ? acc[i] * __expf(Gn[ni] - g0j) : 0.f, v1 = ni <= nj ? acc[i] * __expf(Gn[64 + ni] - g1j) : 0.f;
;                     q0[ni * 64 + nj] = (bf16_t)f2bf(v0); q1[(63 - ni) * 64 + (63 - nj)] = (bf16_t)f2bf(v1); }
.LBB0_519:
	s_or_b64 exec, exec, s[20:21]
	v_lshlrev_b32_e32 v6, 6, v0
	v_or_b32_e32 v0, v6, v24
	s_add_u32 s20, s66, s16
	v_bfe_u32 v4, v3, 16, 1
	v_lshlrev_b32_e32 v0, 1, v0
	v_lshrrev_b32_e32 v226, 3, v0
	v_lshlrev_b32_e32 v227, 4, v0
	v_and_b32_e32 v226, 0xf0, v226
	v_and_b32_e32 v227, 0x700, v227
	v_and_b32_e32 v0, 0x180f, v0
	v_or3_b32 v0, v0, v226, v227
	s_addc_u32 s21, s67, s17
	v_add3_u32 v3, v3, v4, s71
	v_lshl_add_u64 v[4:5], s[20:21], 0, v[0:1]
	v_bfe_u32 v0, v2, 16, 1
	s_movk_i32 s20, 0xd7f
	v_add_co_u32_e32 v4, vcc, 0x2646a000, v4
	v_add3_u32 v0, v2, v0, s71
	v_bitop3_b32 v2, v6, s20, v24 bitop3:0x36
	v_addc_co_u32_e32 v5, vcc, 0, v5, vcc
	v_lshlrev_b32_e32 v2, 1, v2
	v_add_u32_e32 v2, 1280, v2
	v_lshrrev_b32_e32 v226, 3, v2
	v_lshlrev_b32_e32 v227, 4, v2
	v_and_b32_e32 v226, 0xf0, v226
	v_and_b32_e32 v227, 0x700, v227
	v_and_b32_e32 v2, 0x180f, v2
	v_or3_b32 v2, v2, v226, v227
	global_store_short_d16_hi v[4:5], v3, off
	global_store_short_d16_hi v2, v0, s[44:45]
	v_or_b32_e32 v0, 18, v25
	v_cmp_ge_u32_e32 vcc, v0, v24
	v_mov_b32_e32 v2, 0
	v_mov_b32_e32 v3, 0
	s_and_saveexec_b64 s[20:21], vcc
	s_cbranch_execz .LBB0_521
	ds_read_b32 v3, v26 offset:72
	s_waitcnt lgkmcnt(0)
	v_sub_f32_e32 v3, v3, v22
	v_mul_f32_e32 v3, 0x3fb8aa3b, v3
	v_exp_f32_e32 v3, v3
	s_nop 0
	v_mul_f32_e32 v3, v12, v3

; DI unsigned f2bf(float f) { unsigned u = __float_as_uint(f); return (u + 0x7fffu + ((u >> 16) & 1u)) >> 16; }
; DI void phase_dn_chunkprep(PrmC p, unsigned char* smem, int vb, int nvb) {
;     ...
;                 bf16_t* q0 = DQK + ((size_t)item * 64) * 64; bf16_t* q1 = DQK + ((size_t)(1152 + item) * 64) * 64;
; #pragma unroll
;                 for (int i = 0; i < 16; ++i) { const int ni = 32 * it + (i & 3) + 8 * (i >> 2) + 4 * hh;
;                     const float v0 = ni >= nj ? acc[i] * __expf(Gn[ni] - g0j) : 0.f, v1 = ni <= nj ? acc[i] * __expf(Gn[64 + ni] - g1j) : 0.f;
;                     q0[ni * 64 + nj] = (bf16_t)f2bf(v0); q1[(63 - ni) * 64 + (63 - nj)] = (bf16_t)f2bf(v1); }
.LBB0_523:
	s_or_b64 exec, exec, s[20:21]
	v_lshlrev_b32_e32 v6, 6, v0
	v_or_b32_e32 v0, v6, v24
	s_add_u32 s20, s66, s16
	v_bfe_u32 v4, v3, 16, 1
	v_lshlrev_b32_e32 v0, 1, v0
	v_lshrrev_b32_e32 v226, 3, v0
	v_lshlrev_b32_e32 v227, 4, v0
	v_and_b32_e32 v226, 0xf0, v226
	v_and_b32_e32 v227, 0x700, v227
	v_and_b32_e32 v0, 0x180f, v0
	v_or3_b32 v0, v0, v226, v227
	s_addc_u32 s21, s67, s17
	v_add3_u32 v3, v3, v4, s71
	v_lshl_add_u64 v[4:5], s[20:21], 0, v[0:1]
	v_bfe_u32 v0, v2, 16, 1
	s_movk_i32 s20, 0xdbf
	v_add_co_u32_e32 v4, vcc, 0x2646a000, v4
	v_add3_u32 v0, v2, v0, s71
	v_bitop3_b32 v2, v6, s20, v24 bitop3:0x36
	v_addc_co_u32_e32 v5, vcc, 0, v5, vcc
	v_lshlrev_b32_e32 v2, 1, v2
	v_add_u32_e32 v2, 1152, v2
	v_lshrrev_b32_e32 v226, 3, v2
	v_lshlrev_b32_e32 v227, 4, v2
	v_and_b32_e32 v226, 0xf0, v226
	v_and_b32_e32 v227, 0x700, v227
	v_and_b32_e32 v2, 0x180f, v2
	v_or3_b32 v2, v2, v226, v227
	global_store_short_d16_hi v[4:5], v3, off
	global_store_short_d16_hi v2, v0, s[44:45]
	v_or_b32_e32 v0, 19, v25
	v_cmp_ge_u32_e32 vcc, v0, v24
	v_mov_b32_e32 v2, 0
	v_mov_b32_e32 v3, 0
	s_and_saveexec_b64 s[20:21], vcc
	s_cbranch_execz .LBB0_525
	ds_read_b32 v3, v26 offset:76
	s_waitcnt lgkmcnt(0)
	v_sub_f32_e32 v3, v3, v22
	v_mul_f32_e32 v3, 0x3fb8aa3b, v3
	v_exp_f32_e32 v3, v3
	s_nop 0
	v_mul_f32_e32 v3, v13, v3

; DI unsigned f2bf(float f) { unsigned u = __float_as_uint(f); return (u + 0x7fffu + ((u >> 16) & 1u)) >> 16; }
; DI void phase_dn_chunkprep(PrmC p, unsigned char* smem, int vb, int nvb) {
;     ...
;                 bf16_t* q0 = DQK + ((size_t)item * 64) * 64; bf16_t* q1 = DQK + ((size_t)(1152 + item) * 64) * 64;
; #pragma unroll
;                 for (int i = 0; i < 16; ++i) { const int ni = 32 * it + (i & 3) + 8 * (i >> 2) + 4 * hh;
;                     const float v0 = ni >= nj ? acc[i] * __expf(Gn[ni] - g0j) : 0.f, v1 = ni <= nj ? acc[i] * __expf(Gn[64 + ni] - g1j) : 0.f;
;                     q0[ni * 64 + nj] = (bf16_t)f2bf(v0); q1[(63 - ni) * 64 + (63 - nj)] = (bf16_t)f2bf(v1); }
.LBB0_527:
	s_or_b64 exec, exec, s[20:21]
	v_lshlrev_b32_e32 v6, 6, v0
	v_or_b32_e32 v0, v6, v24
	s_add_u32 s20, s66, s16
	v_bfe_u32 v4, v3, 16, 1
	v_lshlrev_b32_e32 v0, 1, v0
	v_lshrrev_b32_e32 v226, 3, v0
	v_lshlrev_b32_e32 v227, 4, v0
	v_and_b32_e32 v226, 0xf0, v226
	v_and_b32_e32 v227, 0x700, v227
	v_and_b32_e32 v0, 0x180f, v0
	v_or3_b32 v0, v0, v226, v227
	s_addc_u32 s21, s67, s17
	v_add3_u32 v3, v3, v4, s71
	v_lshl_add_u64 v[4:5], s[20:21], 0, v[0:1]
	v_bfe_u32 v0, v2, 16, 1
	s_movk_i32 s20, 0xdff
	v_add_co_u32_e32 v4, vcc, 0x2646a000, v4
	v_add3_u32 v0, v2, v0, s71
	v_bitop3_b32 v2, v6, s20, v24 bitop3:0x36
	v_addc_co_u32_e32 v5, vcc, 0, v5, vcc
	v_lshlrev_b32_e32 v2, 1, v2
	v_add_u32_e32 v2, 1024, v2
	v_lshrrev_b32_e32 v226, 3, v2
	v_lshlrev_b32_e32 v227, 4, v2
	v_and_b32_e32 v226, 0xf0, v226
	v_and_b32_e32 v227, 0x700, v227
	v_and_b32_e32 v2, 0x180f, v2
	v_or3_b32 v2, v2, v226, v227
	global_store_short_d16_hi v[4:5], v3, off
	global_store_short_d16_hi v2, v0, s[44:45]
	v_or_b32_e32 v0, 24, v25
	v_cmp_ge_u32_e32 vcc, v0, v24
	v_mov_b32_e32 v2, 0
	v_mov_b32_e32 v3, 0
	s_and_saveexec_b64 s[20:21], vcc
	s_cbranch_execz .LBB0_529
	ds_read_b32 v3, v26 offset:96
	s_waitcnt lgkmcnt(0)
	v_sub_f32_e32 v3, v3, v22
	v_mul_f32_e32 v3, 0x3fb8aa3b, v3
	v_exp_f32_e32 v3, v3
	s_nop 0
	v_mul_f32_e32 v3, v14, v3

; DI unsigned f2bf(float f) { unsigned u = __float_as_uint(f); return (u + 0x7fffu + ((u >> 16) & 1u)) >> 16; }
; DI void phase_dn_chunkprep(PrmC p, unsigned char* smem, int vb, int nvb) {
;     ...
;                 bf16_t* q0 = DQK + ((size_t)item * 64) * 64; bf16_t* q1 = DQK + ((size_t)(1152 + item) * 64) * 64;
; #pragma unroll
;                 for (int i = 0; i < 16; ++i) { const int ni = 32 * it + (i & 3) + 8 * (i >> 2) + 4 * hh;
;                     const float v0 = ni >= nj ? acc[i] * __expf(Gn[ni] - g0j) : 0.f, v1 = ni <= nj ? acc[i] * __expf(Gn[64 + ni] - g1j) : 0.f;
;                     q0[ni * 64 + nj] = (bf16_t)f2bf(v0); q1[(63 - ni) * 64 + (63 - nj)] = (bf16_t)f2bf(v1); }
.LBB0_531:
	s_or_b64 exec, exec, s[20:21]
	v_lshlrev_b32_e32 v6, 6, v0
	v_or_b32_e32 v0, v6, v24
	s_add_u32 s20, s66, s16
	v_bfe_u32 v4, v3, 16, 1
	v_lshlrev_b32_e32 v0, 1, v0
	v_lshrrev_b32_e32 v226, 3, v0
	v_lshlrev_b32_e32 v227, 4, v0
	v_and_b32_e32 v226, 0xf0, v226
	v_and_b32_e32 v227, 0x700, v227
	v_and_b32_e32 v0, 0x180f, v0
	v_or3_b32 v0, v0, v226, v227
	s_addc_u32 s21, s67, s17
	v_add3_u32 v3, v3, v4, s71
	v_lshl_add_u64 v[4:5], s[20:21], 0, v[0:1]
	v_bfe_u32 v0, v2, 16, 1
	s_movk_i32 s20, 0xf3f
	v_add_co_u32_e32 v4, vcc, 0x2646a000, v4
	v_add3_u32 v0, v2, v0, s71
	v_bitop3_b32 v2, v6, s20, v24 bitop3:0x36
	v_addc_co_u32_e32 v5, vcc, 0, v5, vcc
	v_lshlrev_b32_e32 v2, 1, v2
	v_add_u32_e32 v2, 384, v2
	v_lshrrev_b32_e32 v226, 3, v2
	v_lshlrev_b32_e32 v227, 4, v2
	v_and_b32_e32 v226, 0xf0, v226
	v_and_b32_e32 v227, 0x700, v227
	v_and_b32_e32 v2, 0x180f, v2
	v_or3_b32 v2, v2, v226, v227
	global_store_short_d16_hi v[4:5], v3, off
	global_store_short_d16_hi v2, v0, s[44:45]
	v_or_b32_e32 v0, 25, v25
	v_cmp_ge_u32_e32 vcc, v0, v24
	v_mov_b32_e32 v2, 0
	v_mov_b32_e32 v3, 0
	s_and_saveexec_b64 s[20:21], vcc
	s_cbranch_execz .LBB0_533
	ds_read_b32 v3, v26 offset:100
	s_waitcnt lgkmcnt(0)
	v_sub_f32_e32 v3, v3, v22
	v_mul_f32_e32 v3, 0x3fb8aa3b, v3
	v_exp_f32_e32 v3, v3
	s_nop 0
	v_mul_f32_e32 v3, v15, v3

; DI unsigned f2bf(float f) { unsigned u = __float_as_uint(f); return (u + 0x7fffu + ((u >> 16) & 1u)) >> 16; }
; DI void phase_dn_chunkprep(PrmC p, unsigned char* smem, int vb, int nvb) {
;     ...
;                 bf16_t* q0 = DQK + ((size_t)item * 64) * 64; bf16_t* q1 = DQK + ((size_t)(1152 + item) * 64) * 64;
; #pragma unroll
;                 for (int i = 0; i < 16; ++i) { const int ni = 32 * it + (i & 3) + 8 * (i >> 2) + 4 * hh;
;                     const float v0 = ni >= nj ? acc[i] * __expf(Gn[ni] - g0j) : 0.f, v1 = ni <= nj ? acc[i] * __expf(Gn[64 + ni] - g1j) : 0.f;
;                     q0[ni * 64 + nj] = (bf16_t)f2bf(v0); q1[(63 - ni) * 64 + (63 - nj)] = (bf16_t)f2bf(v1); }
.LBB0_535:
	s_or_b64 exec, exec, s[20:21]
	v_lshlrev_b32_e32 v6, 6, v0
	v_or_b32_e32 v0, v6, v24
	s_add_u32 s20, s66, s16
	v_bfe_u32 v4, v3, 16, 1
	v_lshlrev_b32_e32 v0, 1, v0
	v_lshrrev_b32_e32 v226, 3, v0
	v_lshlrev_b32_e32 v227, 4, v0
	v_and_b32_e32 v226, 0xf0, v226
	v_and_b32_e32 v227, 0x700, v227
	v_and_b32_e32 v0, 0x180f, v0
	v_or3_b32 v0, v0, v226, v227
	s_addc_u32 s21, s67, s17
	v_add3_u32 v3, v3, v4, s71
	v_lshl_add_u64 v[4:5], s[20:21], 0, v[0:1]
	v_bfe_u32 v0, v2, 16, 1
	s_movk_i32 s20, 0xf7f
	v_add_co_u32_e32 v4, vcc, 0x2646a000, v4
	v_add3_u32 v0, v2, v0, s71
	v_bitop3_b32 v2, v6, s20, v24 bitop3:0x36
	v_addc_co_u32_e32 v5, vcc, 0, v5, vcc
	v_lshlrev_b32_e32 v2, 1, v2
	v_add_u32_e32 v2, 256, v2
	v_lshrrev_b32_e32 v226, 3, v2
	v_lshlrev_b32_e32 v227, 4, v2
	v_and_b32_e32 v226, 0xf0, v226
	v_and_b32_e32 v227, 0x700, v227
	v_and_b32_e32 v2, 0x180f, v2
	v_or3_b32 v2, v2, v226, v227
	global_store_short_d16_hi v[4:5], v3, off
	global_store_short_d16_hi v2, v0, s[44:45]
	v_or_b32_e32 v0, 26, v25
	v_cmp_ge_u32_e32 vcc, v0, v24
	v_mov_b32_e32 v2, 0
	v_mov_b32_e32 v3, 0
	s_and_saveexec_b64 s[20:21], vcc
	s_cbranch_execz .LBB0_537
	ds_read_b32 v3, v26 offset:104
	s_waitcnt lgkmcnt(0)
	v_sub_f32_e32 v3, v3, v22
	v_mul_f32_e32 v3, 0x3fb8aa3b, v3
	v_exp_f32_e32 v3, v3
	s_nop 0
	v_mul_f32_e32 v3, v16, v3

; DI unsigned f2bf(float f) { unsigned u = __float_as_uint(f); return (u + 0x7fffu + ((u >> 16) & 1u)) >> 16; }
; DI void phase_dn_chunkprep(PrmC p, unsigned char* smem, int vb, int nvb) {
;     ...
;                 bf16_t* q0 = DQK + ((size_t)item * 64) * 64; bf16_t* q1 = DQK + ((size_t)(1152 + item) * 64) * 64;
; #pragma unroll
;                 for (int i = 0; i < 16; ++i) { const int ni = 32 * it + (i & 3) + 8 * (i >> 2) + 4 * hh;
;                     const float v0 = ni >= nj ? acc[i] * __expf(Gn[ni] - g0j) : 0.f, v1 = ni <= nj ? acc[i] * __expf(Gn[64 + ni] - g1j) : 0.f;
;                     q0[ni * 64 + nj] = (bf16_t)f2bf(v0); q1[(63 - ni) * 64 + (63 - nj)] = (bf16_t)f2bf(v1); }
.LBB0_539:
	s_or_b64 exec, exec, s[20:21]
	v_lshlrev_b32_e32 v6, 6, v0
	v_or_b32_e32 v0, v6, v24
	s_add_u32 s20, s66, s16
	v_bfe_u32 v4, v3, 16, 1
	v_lshlrev_b32_e32 v0, 1, v0
	v_lshrrev_b32_e32 v226, 3, v0
	v_lshlrev_b32_e32 v227, 4, v0
	v_and_b32_e32 v226, 0xf0, v226
	v_and_b32_e32 v227, 0x700, v227
	v_and_b32_e32 v0, 0x180f, v0
	v_or3_b32 v0, v0, v226, v227
	s_addc_u32 s21, s67, s17
	v_add3_u32 v3, v3, v4, s71
	v_lshl_add_u64 v[4:5], s[20:21], 0, v[0:1]
	v_bfe_u32 v0, v2, 16, 1
	s_movk_i32 s20, 0xfbf
	v_add_co_u32_e32 v4, vcc, 0x2646a000, v4
	v_add3_u32 v0, v2, v0, s71
	v_bitop3_b32 v2, v6, s20, v24 bitop3:0x36
	v_addc_co_u32_e32 v5, vcc, 0, v5, vcc
	v_lshlrev_b32_e32 v2, 1, v2
	v_add_u32_e32 v2, 128, v2
	v_lshrrev_b32_e32 v226, 3, v2
	v_lshlrev_b32_e32 v227, 4, v2
	v_and_b32_e32 v226, 0xf0, v226
	v_and_b32_e32 v227, 0x700, v227
	v_and_b32_e32 v2, 0x180f, v2
	v_or3_b32 v2, v2, v226, v227
	global_store_short_d16_hi v[4:5], v3, off
	global_store_short_d16_hi v2, v0, s[44:45]
	v_or_b32_e32 v0, 27, v25
	v_cmp_ge_u32_e32 vcc, v0, v24
	v_mov_b32_e32 v2, 0
	v_mov_b32_e32 v3, 0
	s_and_saveexec_b64 s[20:21], vcc
	s_cbranch_execz .LBB0_541
	ds_read_b32 v3, v26 offset:108
	s_waitcnt lgkmcnt(0)
	v_sub_f32_e32 v3, v3, v22
	v_mul_f32_e32 v3, 0x3fb8aa3b, v3
	v_exp_f32_e32 v3, v3
	s_nop 0
	v_mul_f32_e32 v3, v17, v3

; DI unsigned f2bf(float f) { unsigned u = __float_as_uint(f); return (u + 0x7fffu + ((u >> 16) & 1u)) >> 16; }
; DI void phase_dn_chunkprep(PrmC p, unsigned char* smem, int vb, int nvb) {
;     ...
;                 bf16_t* q0 = DQK + ((size_t)item * 64) * 64; bf16_t* q1 = DQK + ((size_t)(1152 + item) * 64) * 64;
; #pragma unroll
;                 for (int i = 0; i < 16; ++i) { const int ni = 32 * it + (i & 3) + 8 * (i >> 2) + 4 * hh;
;                     const float v0 = ni >= nj ? acc[i] * __expf(Gn[ni] - g0j) : 0.f, v1 = ni <= nj ? acc[i] * __expf(Gn[64 + ni] - g1j) : 0.f;
;                     q0[ni * 64 + nj] = (bf16_t)f2bf(v0); q1[(63 - ni) * 64 + (63 - nj)] = (bf16_t)f2bf(v1); }
.LBB0_543:
	s_or_b64 exec, exec, s[20:21]
	v_lshlrev_b32_e32 v6, 6, v0
	v_or_b32_e32 v0, v6, v24
	s_add_u32 s20, s66, s16
	v_bfe_u32 v4, v3, 16, 1
	v_lshlrev_b32_e32 v0, 1, v0
	v_lshrrev_b32_e32 v226, 3, v0
	v_lshlrev_b32_e32 v227, 4, v0
	v_and_b32_e32 v226, 0xf0, v226
	v_and_b32_e32 v227, 0x700, v227
	v_and_b32_e32 v0, 0x180f, v0
	v_or3_b32 v0, v0, v226, v227
	s_addc_u32 s21, s67, s17
	v_add3_u32 v3, v3, v4, s71
	v_lshl_add_u64 v[4:5], s[20:21], 0, v[0:1]
	v_bfe_u32 v0, v2, 16, 1
	s_movk_i32 s20, 0xfff
	v_add_co_u32_e32 v4, vcc, 0x2646a000, v4
	v_add3_u32 v0, v2, v0, s71
	v_bitop3_b32 v2, v6, s20, v24 bitop3:0x36
	v_addc_co_u32_e32 v5, vcc, 0, v5, vcc
	v_lshlrev_b32_e32 v2, 1, v2
	v_lshrrev_b32_e32 v226, 3, v2
	v_lshlrev_b32_e32 v227, 4, v2
	v_and_b32_e32 v226, 0xf0, v226
	v_and_b32_e32 v227, 0x700, v227
	v_and_b32_e32 v2, 0x180f, v2
	v_or3_b32 v2, v2, v226, v227
	global_store_short_d16_hi v[4:5], v3, off
	global_store_short_d16_hi v2, v0, s[44:45]
